# RES epilogue row-sum atomics deferred to the end of the epilogue
# speedup vs baseline: 1.0483x; 1.0044x over previous
.LBB0_439:
	s_cmp_lg_u64 s[36:37], 0
	s_cselect_b64 s[20:21], -1, 0
	s_cmp_eq_u64 s[36:37], 0
	s_cbranch_scc1 .LBB0_443
	v_pk_mul_f32 v[124:125], v[124:125], v[124:125]
	v_pk_mul_f32 v[126:127], v[126:127], v[126:127]
	v_add_f32_e32 v124, v124, v125
	v_add_f32_e32 v124, v126, v124
	v_pk_mul_f32 v[120:121], v[120:121], v[120:121]
	v_add_f32_e32 v124, v127, v124
	v_add_f32_e32 v120, v120, v124
	v_pk_mul_f32 v[122:123], v[122:123], v[122:123]
	v_add_f32_e32 v120, v121, v120
	v_add_f32_e32 v120, v122, v120
	v_pk_mul_f32 v[116:117], v[116:117], v[116:117]
	v_add_f32_e32 v120, v123, v120
	v_add_f32_e32 v116, v120, v116
	v_pk_mul_f32 v[118:119], v[118:119], v[118:119]
	v_add_f32_e32 v116, v117, v116
	v_add_f32_e32 v116, v118, v116
	v_pk_mul_f32 v[112:113], v[112:113], v[112:113]
	v_add_f32_e32 v116, v119, v116
	v_add_f32_e32 v112, v112, v116
	v_pk_mul_f32 v[114:115], v[114:115], v[114:115]
	v_add_f32_e32 v112, v113, v112
	v_add_f32_e32 v112, v114, v112
	v_and_b32_e32 v114, 64, v205
	v_xor_b32_e32 v113, 16, v205
	v_add_u32_e32 v114, 64, v114
	v_cmp_lt_i32_e32 vcc, v113, v114
	v_add_f32_e32 v112, v115, v112
	s_nop 0
	v_cndmask_b32_e32 v113, v205, v113, vcc
	v_lshlrev_b32_e32 v113, 2, v113
	ds_bpermute_b32 v113, v113, v112
	s_waitcnt lgkmcnt(0)
	v_add_f32_e32 v112, v112, v113
	v_xor_b32_e32 v113, 32, v205
	v_cmp_lt_i32_e32 vcc, v113, v114
	s_nop 1
	v_cndmask_b32_e32 v113, v205, v113, vcc
	v_lshlrev_b32_e32 v113, 2, v113
	ds_bpermute_b32 v113, v113, v112
	s_mov_b64 s[14:15], exec
	v_readlane_b32 s16, v254, 33
	v_readlane_b32 s17, v254, 34
	s_and_b64 s[16:17], s[14:15], s[16:17]
	s_mov_b64 exec, s[16:17]
	s_cbranch_execz .LBB0_442
	s_waitcnt lgkmcnt(0)
	v_add_f32_e32 v112, v112, v113
	v_mov_b32_e32 v244, v112

.LBB0_457:
	v_cndmask_b32_e64 v128, 0, 1, s[20:21]
	v_cmp_ne_u32_e64 s[14:15], 1, v128
	s_andn2_b64 vcc, exec, s[20:21]
	s_cbranch_vccnz .LBB0_461
	v_pk_mul_f32 v[108:109], v[108:109], v[108:109]
	v_pk_mul_f32 v[110:111], v[110:111], v[110:111]
	v_add_f32_e32 v108, v108, v109
	v_add_f32_e32 v108, v110, v108
	v_pk_mul_f32 v[104:105], v[104:105], v[104:105]
	v_add_f32_e32 v108, v111, v108
	v_add_f32_e32 v104, v104, v108
	v_pk_mul_f32 v[106:107], v[106:107], v[106:107]
	v_add_f32_e32 v104, v105, v104
	v_add_f32_e32 v104, v106, v104
	v_pk_mul_f32 v[100:101], v[100:101], v[100:101]
	v_add_f32_e32 v104, v107, v104
	v_add_f32_e32 v100, v104, v100
	v_pk_mul_f32 v[102:103], v[102:103], v[102:103]
	v_add_f32_e32 v100, v101, v100
	v_add_f32_e32 v100, v102, v100
	v_pk_mul_f32 v[96:97], v[96:97], v[96:97]
	v_add_f32_e32 v100, v103, v100
	v_add_f32_e32 v96, v96, v100
	v_pk_mul_f32 v[98:99], v[98:99], v[98:99]
	v_add_f32_e32 v96, v97, v96
	v_add_f32_e32 v96, v98, v96
	v_and_b32_e32 v98, 64, v205
	v_xor_b32_e32 v97, 16, v205
	v_add_u32_e32 v98, 64, v98
	v_cmp_lt_i32_e32 vcc, v97, v98
	v_add_f32_e32 v96, v99, v96
	s_nop 0
	v_cndmask_b32_e32 v97, v205, v97, vcc
	v_lshlrev_b32_e32 v97, 2, v97
	ds_bpermute_b32 v97, v97, v96
	s_waitcnt lgkmcnt(0)
	v_add_f32_e32 v96, v96, v97
	v_xor_b32_e32 v97, 32, v205
	v_cmp_lt_i32_e32 vcc, v97, v98
	s_nop 1
	v_cndmask_b32_e32 v97, v205, v97, vcc
	v_lshlrev_b32_e32 v97, 2, v97
	ds_bpermute_b32 v97, v97, v96
	s_mov_b64 s[20:21], exec
	v_readlane_b32 s16, v254, 33
	v_readlane_b32 s17, v254, 34
	s_and_b64 s[16:17], s[20:21], s[16:17]
	s_mov_b64 exec, s[16:17]
	s_cbranch_execz .LBB0_460
	s_waitcnt lgkmcnt(0)
	v_add_f32_e32 v96, v96, v97
	v_mov_b32_e32 v245, v96

.LBB0_475:
	s_and_b64 vcc, exec, s[14:15]
	s_cbranch_vccnz .LBB0_479
	v_pk_mul_f32 v[92:93], v[92:93], v[92:93]
	v_pk_mul_f32 v[94:95], v[94:95], v[94:95]
	v_add_f32_e32 v92, v92, v93
	v_add_f32_e32 v92, v94, v92
	v_pk_mul_f32 v[88:89], v[88:89], v[88:89]
	v_add_f32_e32 v92, v95, v92
	v_add_f32_e32 v88, v88, v92
	v_pk_mul_f32 v[90:91], v[90:91], v[90:91]
	v_add_f32_e32 v88, v89, v88
	v_add_f32_e32 v88, v90, v88
	v_pk_mul_f32 v[84:85], v[84:85], v[84:85]
	v_add_f32_e32 v88, v91, v88
	v_add_f32_e32 v84, v88, v84
	v_pk_mul_f32 v[86:87], v[86:87], v[86:87]
	v_add_f32_e32 v84, v85, v84
	v_add_f32_e32 v84, v86, v84
	v_pk_mul_f32 v[80:81], v[80:81], v[80:81]
	v_add_f32_e32 v84, v87, v84
	v_add_f32_e32 v80, v80, v84
	v_pk_mul_f32 v[82:83], v[82:83], v[82:83]
	v_add_f32_e32 v80, v81, v80
	v_add_f32_e32 v80, v82, v80
	v_and_b32_e32 v82, 64, v205
	v_xor_b32_e32 v81, 16, v205
	v_add_u32_e32 v82, 64, v82
	v_cmp_lt_i32_e32 vcc, v81, v82
	v_add_f32_e32 v80, v83, v80
	s_nop 0
	v_cndmask_b32_e32 v81, v205, v81, vcc
	v_lshlrev_b32_e32 v81, 2, v81
	ds_bpermute_b32 v81, v81, v80
	s_waitcnt lgkmcnt(0)
	v_add_f32_e32 v80, v80, v81
	v_xor_b32_e32 v81, 32, v205
	v_cmp_lt_i32_e32 vcc, v81, v82
	s_nop 1
	v_cndmask_b32_e32 v81, v205, v81, vcc
	v_lshlrev_b32_e32 v81, 2, v81
	ds_bpermute_b32 v81, v81, v80
	s_mov_b64 s[20:21], exec
	v_readlane_b32 s16, v254, 33
	v_readlane_b32 s17, v254, 34
	s_and_b64 s[16:17], s[20:21], s[16:17]
	s_mov_b64 exec, s[16:17]
	s_cbranch_execz .LBB0_478
	s_waitcnt lgkmcnt(0)
	v_add_f32_e32 v80, v80, v81
	v_mov_b32_e32 v246, v80

.LBB0_493:
	s_and_b64 vcc, exec, s[14:15]
	s_cbranch_vccnz .LBB0_497
	v_pk_mul_f32 v[76:77], v[76:77], v[76:77]
	v_pk_mul_f32 v[78:79], v[78:79], v[78:79]
	v_add_f32_e32 v76, v76, v77
	v_add_f32_e32 v76, v78, v76
	v_pk_mul_f32 v[72:73], v[72:73], v[72:73]
	v_add_f32_e32 v76, v79, v76
	v_add_f32_e32 v72, v72, v76
	v_pk_mul_f32 v[74:75], v[74:75], v[74:75]
	v_add_f32_e32 v72, v73, v72
	v_add_f32_e32 v72, v74, v72
	v_pk_mul_f32 v[68:69], v[68:69], v[68:69]
	v_add_f32_e32 v72, v75, v72
	v_add_f32_e32 v68, v72, v68
	v_pk_mul_f32 v[70:71], v[70:71], v[70:71]
	v_add_f32_e32 v68, v69, v68
	v_add_f32_e32 v68, v70, v68
	v_pk_mul_f32 v[64:65], v[64:65], v[64:65]
	v_add_f32_e32 v68, v71, v68
	v_add_f32_e32 v64, v64, v68
	v_pk_mul_f32 v[66:67], v[66:67], v[66:67]
	v_add_f32_e32 v64, v65, v64
	v_add_f32_e32 v64, v66, v64
	v_and_b32_e32 v66, 64, v205
	v_xor_b32_e32 v65, 16, v205
	v_add_u32_e32 v66, 64, v66
	v_cmp_lt_i32_e32 vcc, v65, v66
	v_add_f32_e32 v64, v67, v64
	s_nop 0
	v_cndmask_b32_e32 v65, v205, v65, vcc
	v_lshlrev_b32_e32 v65, 2, v65
	ds_bpermute_b32 v65, v65, v64
	s_waitcnt lgkmcnt(0)
	v_add_f32_e32 v64, v64, v65
	v_xor_b32_e32 v65, 32, v205
	v_cmp_lt_i32_e32 vcc, v65, v66
	s_nop 1
	v_cndmask_b32_e32 v65, v205, v65, vcc
	v_lshlrev_b32_e32 v65, 2, v65
	ds_bpermute_b32 v65, v65, v64
	s_mov_b64 s[20:21], exec
	v_readlane_b32 s16, v254, 33
	v_readlane_b32 s17, v254, 34
	s_and_b64 s[16:17], s[20:21], s[16:17]
	s_mov_b64 exec, s[16:17]
	s_cbranch_execz .LBB0_496
	s_waitcnt lgkmcnt(0)
	v_add_f32_e32 v64, v64, v65
	v_mov_b32_e32 v247, v64

.LBB0_511:
	s_and_b64 vcc, exec, s[14:15]
	s_cbranch_vccnz .LBB0_515
	v_pk_mul_f32 v[60:61], v[60:61], v[60:61]
	v_pk_mul_f32 v[62:63], v[62:63], v[62:63]
	v_add_f32_e32 v60, v60, v61
	v_add_f32_e32 v60, v62, v60
	v_pk_mul_f32 v[56:57], v[56:57], v[56:57]
	v_add_f32_e32 v60, v63, v60
	v_add_f32_e32 v56, v56, v60
	v_pk_mul_f32 v[58:59], v[58:59], v[58:59]
	v_add_f32_e32 v56, v57, v56
	v_add_f32_e32 v56, v58, v56
	v_pk_mul_f32 v[52:53], v[52:53], v[52:53]
	v_add_f32_e32 v56, v59, v56
	v_add_f32_e32 v52, v56, v52
	v_pk_mul_f32 v[54:55], v[54:55], v[54:55]
	v_add_f32_e32 v52, v53, v52
	v_add_f32_e32 v52, v54, v52
	v_pk_mul_f32 v[48:49], v[48:49], v[48:49]
	v_add_f32_e32 v52, v55, v52
	v_add_f32_e32 v48, v48, v52
	v_pk_mul_f32 v[50:51], v[50:51], v[50:51]
	v_add_f32_e32 v48, v49, v48
	v_add_f32_e32 v48, v50, v48
	v_and_b32_e32 v50, 64, v205
	v_xor_b32_e32 v49, 16, v205
	v_add_u32_e32 v50, 64, v50
	v_cmp_lt_i32_e32 vcc, v49, v50
	v_add_f32_e32 v48, v51, v48
	s_nop 0
	v_cndmask_b32_e32 v49, v205, v49, vcc
	v_lshlrev_b32_e32 v49, 2, v49
	ds_bpermute_b32 v49, v49, v48
	s_waitcnt lgkmcnt(0)
	v_add_f32_e32 v48, v48, v49
	v_xor_b32_e32 v49, 32, v205
	v_cmp_lt_i32_e32 vcc, v49, v50
	s_nop 1
	v_cndmask_b32_e32 v49, v205, v49, vcc
	v_lshlrev_b32_e32 v49, 2, v49
	ds_bpermute_b32 v49, v49, v48
	s_mov_b64 s[20:21], exec
	v_readlane_b32 s16, v254, 33
	v_readlane_b32 s17, v254, 34
	s_and_b64 s[16:17], s[20:21], s[16:17]
	s_mov_b64 exec, s[16:17]
	s_cbranch_execz .LBB0_514
	s_waitcnt lgkmcnt(0)
	v_add_f32_e32 v48, v48, v49
	v_mov_b32_e32 v248, v48

.LBB0_529:
	s_and_b64 vcc, exec, s[14:15]
	s_cbranch_vccnz .LBB0_533
	v_pk_mul_f32 v[44:45], v[44:45], v[44:45]
	v_pk_mul_f32 v[46:47], v[46:47], v[46:47]
	v_add_f32_e32 v44, v44, v45
	v_add_f32_e32 v44, v46, v44
	v_pk_mul_f32 v[40:41], v[40:41], v[40:41]
	v_add_f32_e32 v44, v47, v44
	v_add_f32_e32 v40, v40, v44
	v_pk_mul_f32 v[42:43], v[42:43], v[42:43]
	v_add_f32_e32 v40, v41, v40
	v_add_f32_e32 v40, v42, v40
	v_pk_mul_f32 v[36:37], v[36:37], v[36:37]
	v_add_f32_e32 v40, v43, v40
	v_add_f32_e32 v36, v40, v36
	v_pk_mul_f32 v[38:39], v[38:39], v[38:39]
	v_add_f32_e32 v36, v37, v36
	v_add_f32_e32 v36, v38, v36
	v_pk_mul_f32 v[32:33], v[32:33], v[32:33]
	v_add_f32_e32 v36, v39, v36
	v_add_f32_e32 v32, v32, v36
	v_pk_mul_f32 v[34:35], v[34:35], v[34:35]
	v_add_f32_e32 v32, v33, v32
	v_add_f32_e32 v32, v34, v32
	v_and_b32_e32 v34, 64, v205
	v_xor_b32_e32 v33, 16, v205
	v_add_u32_e32 v34, 64, v34
	v_cmp_lt_i32_e32 vcc, v33, v34
	v_add_f32_e32 v32, v35, v32
	s_nop 0
	v_cndmask_b32_e32 v33, v205, v33, vcc
	v_lshlrev_b32_e32 v33, 2, v33
	ds_bpermute_b32 v33, v33, v32
	s_waitcnt lgkmcnt(0)
	v_add_f32_e32 v32, v32, v33
	v_xor_b32_e32 v33, 32, v205
	v_cmp_lt_i32_e32 vcc, v33, v34
	s_nop 1
	v_cndmask_b32_e32 v33, v205, v33, vcc
	v_lshlrev_b32_e32 v33, 2, v33
	ds_bpermute_b32 v33, v33, v32
	s_mov_b64 s[20:21], exec
	v_readlane_b32 s16, v254, 33
	v_readlane_b32 s17, v254, 34
	s_and_b64 s[16:17], s[20:21], s[16:17]
	s_mov_b64 exec, s[16:17]
	s_cbranch_execz .LBB0_532
	s_waitcnt lgkmcnt(0)
	v_add_f32_e32 v32, v32, v33
	v_mov_b32_e32 v249, v32

.LBB0_547:
	s_and_b64 vcc, exec, s[14:15]
	s_cbranch_vccnz .LBB0_551
	v_pk_mul_f32 v[28:29], v[28:29], v[28:29]
	v_pk_mul_f32 v[30:31], v[30:31], v[30:31]
	v_add_f32_e32 v28, v28, v29
	v_add_f32_e32 v28, v30, v28
	v_pk_mul_f32 v[24:25], v[24:25], v[24:25]
	v_add_f32_e32 v28, v31, v28
	v_add_f32_e32 v24, v24, v28
	v_pk_mul_f32 v[26:27], v[26:27], v[26:27]
	v_add_f32_e32 v24, v25, v24
	v_add_f32_e32 v24, v26, v24
	v_pk_mul_f32 v[20:21], v[20:21], v[20:21]
	v_add_f32_e32 v24, v27, v24
	v_add_f32_e32 v20, v24, v20
	v_pk_mul_f32 v[22:23], v[22:23], v[22:23]
	v_add_f32_e32 v20, v21, v20
	v_add_f32_e32 v20, v22, v20
	v_pk_mul_f32 v[16:17], v[16:17], v[16:17]
	v_add_f32_e32 v20, v23, v20
	v_add_f32_e32 v16, v16, v20
	v_pk_mul_f32 v[18:19], v[18:19], v[18:19]
	v_add_f32_e32 v16, v17, v16
	v_add_f32_e32 v16, v18, v16
	v_and_b32_e32 v18, 64, v205
	v_xor_b32_e32 v17, 16, v205
	v_add_u32_e32 v18, 64, v18
	v_cmp_lt_i32_e32 vcc, v17, v18
	v_add_f32_e32 v16, v19, v16
	s_nop 0
	v_cndmask_b32_e32 v17, v205, v17, vcc
	v_lshlrev_b32_e32 v17, 2, v17
	ds_bpermute_b32 v17, v17, v16
	s_waitcnt lgkmcnt(0)
	v_add_f32_e32 v16, v16, v17
	v_xor_b32_e32 v17, 32, v205
	v_cmp_lt_i32_e32 vcc, v17, v18
	s_nop 1
	v_cndmask_b32_e32 v17, v205, v17, vcc
	v_lshlrev_b32_e32 v17, 2, v17
	ds_bpermute_b32 v17, v17, v16
	s_mov_b64 s[12:13], exec
	v_readlane_b32 s16, v254, 33
	v_readlane_b32 s17, v254, 34
	s_and_b64 s[16:17], s[12:13], s[16:17]
	s_mov_b64 exec, s[16:17]
	s_cbranch_execz .LBB0_550
	s_waitcnt lgkmcnt(0)
	v_add_f32_e32 v16, v16, v17
	v_mov_b32_e32 v250, v16

.LBB0_565:
	s_and_b64 vcc, exec, s[14:15]
	s_cbranch_vccnz .LBB0_397
	v_pk_mul_f32 v[12:13], v[12:13], v[12:13]
	v_pk_mul_f32 v[14:15], v[14:15], v[14:15]
	v_add_f32_e32 v12, v12, v13
	v_add_f32_e32 v12, v14, v12
	v_pk_mul_f32 v[8:9], v[8:9], v[8:9]
	v_add_f32_e32 v12, v15, v12
	v_add_f32_e32 v8, v8, v12
	v_pk_mul_f32 v[10:11], v[10:11], v[10:11]
	v_add_f32_e32 v8, v9, v8
	v_add_f32_e32 v8, v10, v8
	v_pk_mul_f32 v[4:5], v[4:5], v[4:5]
	v_add_f32_e32 v8, v11, v8
	v_add_f32_e32 v4, v8, v4
	v_pk_mul_f32 v[6:7], v[6:7], v[6:7]
	v_add_f32_e32 v4, v5, v4
	v_add_f32_e32 v4, v6, v4
	v_pk_mul_f32 v[0:1], v[0:1], v[0:1]
	v_add_f32_e32 v4, v7, v4
	v_add_f32_e32 v0, v0, v4
	v_pk_mul_f32 v[2:3], v[2:3], v[2:3]
	v_add_f32_e32 v0, v1, v0
	v_add_f32_e32 v0, v2, v0
	v_and_b32_e32 v2, 64, v205
	v_xor_b32_e32 v1, 16, v205
	v_add_u32_e32 v2, 64, v2
	v_cmp_lt_i32_e32 vcc, v1, v2
	v_add_f32_e32 v0, v3, v0
	s_nop 0
	v_cndmask_b32_e32 v1, v205, v1, vcc
	v_lshlrev_b32_e32 v1, 2, v1
	ds_bpermute_b32 v1, v1, v0
	s_waitcnt lgkmcnt(0)
	v_add_f32_e32 v0, v0, v1
	v_xor_b32_e32 v1, 32, v205
	v_cmp_lt_i32_e32 vcc, v1, v2
	s_nop 1
	v_cndmask_b32_e32 v1, v205, v1, vcc
	v_lshlrev_b32_e32 v1, 2, v1
	ds_bpermute_b32 v1, v1, v0
	s_mov_b64 s[8:9], exec
	v_readlane_b32 s10, v254, 33
	v_readlane_b32 s11, v254, 34
	s_and_b64 s[10:11], s[8:9], s[10:11]
	s_mov_b64 exec, s[10:11]
	s_cbranch_execz .LBB0_396
	s_waitcnt lgkmcnt(0)
	v_add_f32_e32 v0, v0, v1
	v_mov_b32_e32 v251, v0
	s_mov_b32 s3, 0x49800000
	v_fma_f32 v0, v244, s3, 0.5
	v_trunc_f32_e32 v0, v0
	v_mul_f32_e32 v1, 0x2f800000, v0
	v_floor_f32_e32 v1, v1
	v_fmac_f32_e32 v0, 0xcf800000, v1
	v_cvt_u32_f32_e32 v0, v0
	v_cvt_u32_f32_e32 v1, v1
	v_lshl_add_u64 v[2:3], v[182:183], 3, s[36:37]
	global_atomic_add_x2 v[2:3], v[0:1], off
	v_fma_f32 v4, v245, s3, 0.5
	v_trunc_f32_e32 v4, v4
	v_mul_f32_e32 v5, 0x2f800000, v4
	v_floor_f32_e32 v5, v5
	v_fmac_f32_e32 v4, 0xcf800000, v5
	v_cvt_u32_f32_e32 v4, v4
	v_cvt_u32_f32_e32 v5, v5
	v_lshl_add_u64 v[6:7], v[182:183], 3, s[36:37]
	global_atomic_add_x2 v[6:7], v[4:5], off offset:128
	v_fma_f32 v0, v246, s3, 0.5
	v_trunc_f32_e32 v0, v0
	v_mul_f32_e32 v1, 0x2f800000, v0
	v_floor_f32_e32 v1, v1
	v_fmac_f32_e32 v0, 0xcf800000, v1
	v_cvt_u32_f32_e32 v0, v0
	v_cvt_u32_f32_e32 v1, v1
	v_lshl_add_u64 v[2:3], v[182:183], 3, s[36:37]
	global_atomic_add_x2 v[2:3], v[0:1], off offset:256
	v_fma_f32 v4, v247, s3, 0.5
	v_trunc_f32_e32 v4, v4
	v_mul_f32_e32 v5, 0x2f800000, v4
	v_floor_f32_e32 v5, v5
	v_fmac_f32_e32 v4, 0xcf800000, v5
	v_cvt_u32_f32_e32 v4, v4
	v_cvt_u32_f32_e32 v5, v5
	v_lshl_add_u64 v[6:7], v[182:183], 3, s[36:37]
	global_atomic_add_x2 v[6:7], v[4:5], off offset:384
	v_fma_f32 v0, v248, s3, 0.5
	v_trunc_f32_e32 v0, v0
	v_mul_f32_e32 v1, 0x2f800000, v0
	v_floor_f32_e32 v1, v1
	v_fmac_f32_e32 v0, 0xcf800000, v1
	v_cvt_u32_f32_e32 v0, v0
	v_cvt_u32_f32_e32 v1, v1
	v_lshl_add_u64 v[2:3], v[182:183], 3, s[36:37]
	global_atomic_add_x2 v[2:3], v[0:1], off offset:1024
	v_fma_f32 v4, v249, s3, 0.5
	v_trunc_f32_e32 v4, v4
	v_mul_f32_e32 v5, 0x2f800000, v4
	v_floor_f32_e32 v5, v5
	v_fmac_f32_e32 v4, 0xcf800000, v5
	v_cvt_u32_f32_e32 v4, v4
	v_cvt_u32_f32_e32 v5, v5
	v_lshl_add_u64 v[6:7], v[112:113], 3, s[36:37]
	global_atomic_add_x2 v[6:7], v[4:5], off offset:128
	v_fma_f32 v0, v250, s3, 0.5
	v_trunc_f32_e32 v0, v0
	v_mul_f32_e32 v1, 0x2f800000, v0
	v_floor_f32_e32 v1, v1
	v_fmac_f32_e32 v0, 0xcf800000, v1
	v_cvt_u32_f32_e32 v0, v0
	v_cvt_u32_f32_e32 v1, v1
	v_lshl_add_u64 v[2:3], v[112:113], 3, s[36:37]
	global_atomic_add_x2 v[2:3], v[0:1], off offset:256
	v_fma_f32 v4, v251, s3, 0.5
	v_trunc_f32_e32 v4, v4
	v_mul_f32_e32 v5, 0x2f800000, v4
	v_floor_f32_e32 v5, v5
	v_fmac_f32_e32 v4, 0xcf800000, v5
	v_cvt_u32_f32_e32 v4, v4
	v_cvt_u32_f32_e32 v5, v5
	v_lshl_add_u64 v[6:7], v[112:113], 3, s[36:37]
	global_atomic_add_x2 v[6:7], v[4:5], off offset:384
	s_branch .LBB0_396

.LBB0_711:
	s_lshl_b32 s25, s24, 11
	s_and_b32 s25, s25, 0x800
	v_add_u32_e32 v80, s25, v166
	ds_read2_b64 v[140:143], v80 offset1:16
	ds_read2_b64 v[136:139], v80 offset0:32 offset1:48
	ds_read2_b64 v[112:115], v80 offset0:128 offset1:144
	ds_read2_b64 v[80:83], v80 offset0:160 offset1:176
	s_and_b64 s[8:9], s[0:1], s[8:9]
	s_add_u32 s34, s20, 0xc400000
	s_addc_u32 s35, s21, 0
	s_movk_i32 s82, 0xb00
	v_lshl_add_u32 v169, s17, 8, v158
	v_lshl_or_b32 v156, s3, 7, v167
	v_mov_b32_e32 v157, 0
	v_mad_u64_u32 v[156:157], s[42:43], v169, s82, v[156:157]
	s_mov_b32 s82, 0xbfb8aa3b
	s_mov_b32 s38, 1.0
	s_mov_b32 s30, 0x6e000
	s_mov_b32 s31, 0
	v_lshl_add_u64 v[156:157], v[156:157], 1, s[34:35]
	s_mov_b32 s20, 0x16000
	s_mov_b32 s21, 0
	s_waitcnt lgkmcnt(0)
	v_ffbh_u32_e32 v186, v141
	v_ffbh_u32_e32 v187, v143
	v_ffbh_u32_e32 v188, v137
	v_ffbh_u32_e32 v189, v139
	v_ffbh_u32_e32 v190, v113
	v_ffbh_u32_e32 v191, v115
	v_ffbh_u32_e32 v192, v81
	v_ffbh_u32_e32 v193, v83
	v_min_u32_e32 v186, 32, v186
	v_min_u32_e32 v187, 32, v187
	v_min_u32_e32 v188, 32, v188
	v_min_u32_e32 v189, 32, v189
	v_min_u32_e32 v190, 32, v190
	v_min_u32_e32 v191, 32, v191
	v_min_u32_e32 v192, 32, v192
	v_min_u32_e32 v193, 32, v193
	v_lshlrev_b64 v[140:141], v186, v[140:141]
	v_lshlrev_b64 v[142:143], v187, v[142:143]
	v_lshlrev_b64 v[136:137], v188, v[136:137]
	v_lshlrev_b64 v[138:139], v189, v[138:139]
	v_lshlrev_b64 v[112:113], v190, v[112:113]
	v_lshlrev_b64 v[114:115], v191, v[114:115]
	v_lshlrev_b64 v[80:81], v192, v[80:81]
	v_lshlrev_b64 v[82:83], v193, v[82:83]
	v_min_u32_e32 v140, 1, v140
	v_min_u32_e32 v142, 1, v142
	v_min_u32_e32 v136, 1, v136
	v_min_u32_e32 v138, 1, v138
	v_min_u32_e32 v112, 1, v112
	v_min_u32_e32 v114, 1, v114
	v_min_u32_e32 v80, 1, v80
	v_min_u32_e32 v82, 1, v82
	v_or_b32_e32 v140, v141, v140
	v_or_b32_e32 v142, v143, v142
	v_or_b32_e32 v136, v137, v136
	v_or_b32_e32 v138, v139, v138
	v_or_b32_e32 v112, v113, v112
	v_or_b32_e32 v114, v115, v114
	v_or_b32_e32 v80, v81, v80
	v_or_b32_e32 v82, v83, v82
	v_cvt_f32_u32_e32 v140, v140
	v_cvt_f32_u32_e32 v142, v142
	v_cvt_f32_u32_e32 v136, v136
	v_cvt_f32_u32_e32 v138, v138
	v_cvt_f32_u32_e32 v112, v112
	v_cvt_f32_u32_e32 v114, v114
	v_cvt_f32_u32_e32 v80, v80
	v_cvt_f32_u32_e32 v82, v82
	v_sub_u32_e32 v186, 32, v186
	v_sub_u32_e32 v187, 32, v187
	v_sub_u32_e32 v188, 32, v188
	v_sub_u32_e32 v189, 32, v189
	v_sub_u32_e32 v190, 32, v190
	v_sub_u32_e32 v191, 32, v191
	v_sub_u32_e32 v192, 32, v192
	v_sub_u32_e32 v193, 32, v193
	v_ldexp_f32 v140, v140, v186
	v_ldexp_f32 v142, v142, v187
	v_ldexp_f32 v136, v136, v188
	v_ldexp_f32 v138, v138, v189
	v_ldexp_f32 v112, v112, v190
	v_ldexp_f32 v114, v114, v191
	v_ldexp_f32 v80, v80, v192
	v_ldexp_f32 v82, v82, v193
	v_mul_f32_e32 v140, 0x35800000, v140
	v_mul_f32_e32 v142, 0x35800000, v142
	v_mul_f32_e32 v136, 0x35800000, v136
	v_mul_f32_e32 v138, 0x35800000, v138
	v_mul_f32_e32 v112, 0x35800000, v112
	v_mul_f32_e32 v114, 0x35800000, v114
	v_mul_f32_e32 v80, 0x35800000, v80
	v_mul_f32_e32 v82, 0x35800000, v82
	v_fmamk_f32 v140, v140, 0x3a800000, v165
	v_fmamk_f32 v142, v142, 0x3a800000, v165
	v_fmamk_f32 v136, v136, 0x3a800000, v165
	v_fmamk_f32 v138, v138, 0x3a800000, v165
	v_fmamk_f32 v112, v112, 0x3a800000, v165
	v_fmamk_f32 v114, v114, 0x3a800000, v165
	v_fmamk_f32 v80, v80, 0x3a800000, v165
	v_fmamk_f32 v82, v82, 0x3a800000, v165
	v_rsq_f32_e32 v140, v140
	v_rsq_f32_e32 v142, v142
	v_rsq_f32_e32 v136, v136
	v_rsq_f32_e32 v138, v138
	v_rsq_f32_e32 v112, v112
	v_rsq_f32_e32 v114, v114
	v_rsq_f32_e32 v80, v80
	v_rsq_f32_e32 v82, v82
	v_pk_mul_f32 v[132:133], v[132:133], v[140:141] op_sel_hi:[1,0]
	v_pk_mul_f32 v[134:135], v[134:135], v[140:141] op_sel_hi:[1,0]
	v_pk_mul_f32 v[124:125], v[124:125], v[140:141] op_sel_hi:[1,0]
	v_pk_mul_f32 v[126:127], v[126:127], v[140:141] op_sel_hi:[1,0]
	v_pk_mul_f32 v[128:129], v[128:129], v[140:141] op_sel_hi:[1,0]
	v_pk_mul_f32 v[130:131], v[130:131], v[140:141] op_sel_hi:[1,0]
	v_pk_mul_f32 v[120:121], v[120:121], v[140:141] op_sel_hi:[1,0]
	v_pk_mul_f32 v[122:123], v[122:123], v[140:141] op_sel_hi:[1,0]
	v_pk_mul_f32 v[170:171], v[132:133], s[82:83] op_sel_hi:[1,0]
	v_pk_mul_f32 v[172:173], v[134:135], s[82:83] op_sel_hi:[1,0]
	v_pk_mul_f32 v[174:175], v[124:125], s[82:83] op_sel_hi:[1,0]
	v_pk_mul_f32 v[176:177], v[126:127], s[82:83] op_sel_hi:[1,0]
	v_exp_f32_e32 v170, v170
	v_exp_f32_e32 v171, v171
	v_exp_f32_e32 v172, v172
	v_exp_f32_e32 v173, v173
	v_exp_f32_e32 v174, v174
	v_exp_f32_e32 v175, v175
	v_exp_f32_e32 v176, v176
	v_exp_f32_e32 v177, v177
	v_pk_add_f32 v[170:171], v[170:171], s[38:39] op_sel_hi:[1,0]
	v_pk_add_f32 v[172:173], v[172:173], s[38:39] op_sel_hi:[1,0]
	v_pk_add_f32 v[174:175], v[174:175], s[38:39] op_sel_hi:[1,0]
	v_pk_add_f32 v[176:177], v[176:177], s[38:39] op_sel_hi:[1,0]
	v_rcp_f32_e32 v170, v170
	v_rcp_f32_e32 v171, v171
	v_rcp_f32_e32 v172, v172
	v_rcp_f32_e32 v173, v173
	v_rcp_f32_e32 v174, v174
	v_rcp_f32_e32 v175, v175
	v_rcp_f32_e32 v176, v176
	v_rcp_f32_e32 v177, v177
	v_pk_mul_f32 v[170:171], v[132:133], v[170:171]
	v_pk_mul_f32 v[172:173], v[134:135], v[172:173]
	v_pk_mul_f32 v[174:175], v[124:125], v[174:175]
	v_pk_mul_f32 v[176:177], v[126:127], v[176:177]
	v_pk_mul_f32 v[170:171], v[128:129], v[170:171]
	v_pk_mul_f32 v[172:173], v[130:131], v[172:173]
	v_pk_mul_f32 v[174:175], v[120:121], v[174:175]
	v_pk_mul_f32 v[176:177], v[122:123], v[176:177]
	v_cvt_pk_bf16_f32 v194, v170, v171
	v_cvt_pk_bf16_f32 v195, v172, v173
	v_cvt_pk_bf16_f32 v196, v174, v175
	v_cvt_pk_bf16_f32 v197, v176, v177
	global_store_dwordx4 v[156:157], v[194:197], off
	v_lshl_add_u64 v[156:157], v[156:157], 0, s[20:21]
	v_pk_mul_f32 v[116:117], v[116:117], v[142:143] op_sel_hi:[1,0]
	v_pk_mul_f32 v[118:119], v[118:119], v[142:143] op_sel_hi:[1,0]
	v_pk_mul_f32 v[104:105], v[104:105], v[142:143] op_sel_hi:[1,0]
	v_pk_mul_f32 v[106:107], v[106:107], v[142:143] op_sel_hi:[1,0]
	v_pk_mul_f32 v[108:109], v[108:109], v[142:143] op_sel_hi:[1,0]
	v_pk_mul_f32 v[110:111], v[110:111], v[142:143] op_sel_hi:[1,0]
	v_pk_mul_f32 v[100:101], v[100:101], v[142:143] op_sel_hi:[1,0]
	v_pk_mul_f32 v[102:103], v[102:103], v[142:143] op_sel_hi:[1,0]
	v_pk_mul_f32 v[178:179], v[116:117], s[82:83] op_sel_hi:[1,0]
	v_pk_mul_f32 v[180:181], v[118:119], s[82:83] op_sel_hi:[1,0]
	v_pk_mul_f32 v[182:183], v[104:105], s[82:83] op_sel_hi:[1,0]
	v_pk_mul_f32 v[184:185], v[106:107], s[82:83] op_sel_hi:[1,0]
	v_exp_f32_e32 v178, v178
	v_exp_f32_e32 v179, v179
	v_exp_f32_e32 v180, v180
	v_exp_f32_e32 v181, v181
	v_exp_f32_e32 v182, v182
	v_exp_f32_e32 v183, v183
	v_exp_f32_e32 v184, v184
	v_exp_f32_e32 v185, v185
	v_pk_add_f32 v[178:179], v[178:179], s[38:39] op_sel_hi:[1,0]
	v_pk_add_f32 v[180:181], v[180:181], s[38:39] op_sel_hi:[1,0]
	v_pk_add_f32 v[182:183], v[182:183], s[38:39] op_sel_hi:[1,0]
	v_pk_add_f32 v[184:185], v[184:185], s[38:39] op_sel_hi:[1,0]
	v_rcp_f32_e32 v178, v178
	v_rcp_f32_e32 v179, v179
	v_rcp_f32_e32 v180, v180
	v_rcp_f32_e32 v181, v181
	v_rcp_f32_e32 v182, v182
	v_rcp_f32_e32 v183, v183
	v_rcp_f32_e32 v184, v184
	v_rcp_f32_e32 v185, v185
	v_pk_mul_f32 v[178:179], v[116:117], v[178:179]
	v_pk_mul_f32 v[180:181], v[118:119], v[180:181]
	v_pk_mul_f32 v[182:183], v[104:105], v[182:183]
	v_pk_mul_f32 v[184:185], v[106:107], v[184:185]
	v_pk_mul_f32 v[178:179], v[108:109], v[178:179]
	v_pk_mul_f32 v[180:181], v[110:111], v[180:181]
	v_pk_mul_f32 v[182:183], v[100:101], v[182:183]
	v_pk_mul_f32 v[184:185], v[102:103], v[184:185]
	v_cvt_pk_bf16_f32 v198, v178, v179
	v_cvt_pk_bf16_f32 v199, v180, v181
	v_cvt_pk_bf16_f32 v200, v182, v183
	v_cvt_pk_bf16_f32 v201, v184, v185
	global_store_dwordx4 v[156:157], v[198:201], off
	v_lshl_add_u64 v[156:157], v[156:157], 0, s[20:21]
	v_pk_mul_f32 v[96:97], v[96:97], v[136:137] op_sel_hi:[1,0]
	v_pk_mul_f32 v[98:99], v[98:99], v[136:137] op_sel_hi:[1,0]
	v_pk_mul_f32 v[88:89], v[88:89], v[136:137] op_sel_hi:[1,0]
	v_pk_mul_f32 v[90:91], v[90:91], v[136:137] op_sel_hi:[1,0]
	v_pk_mul_f32 v[92:93], v[92:93], v[136:137] op_sel_hi:[1,0]
	v_pk_mul_f32 v[94:95], v[94:95], v[136:137] op_sel_hi:[1,0]
	v_pk_mul_f32 v[84:85], v[84:85], v[136:137] op_sel_hi:[1,0]
	v_pk_mul_f32 v[86:87], v[86:87], v[136:137] op_sel_hi:[1,0]
	v_pk_mul_f32 v[170:171], v[96:97], s[82:83] op_sel_hi:[1,0]
	v_pk_mul_f32 v[172:173], v[98:99], s[82:83] op_sel_hi:[1,0]
	v_pk_mul_f32 v[174:175], v[88:89], s[82:83] op_sel_hi:[1,0]
	v_pk_mul_f32 v[176:177], v[90:91], s[82:83] op_sel_hi:[1,0]
	v_exp_f32_e32 v170, v170
	v_exp_f32_e32 v171, v171
	v_exp_f32_e32 v172, v172
	v_exp_f32_e32 v173, v173
	v_exp_f32_e32 v174, v174
	v_exp_f32_e32 v175, v175
	v_exp_f32_e32 v176, v176
	v_exp_f32_e32 v177, v177
	v_pk_add_f32 v[170:171], v[170:171], s[38:39] op_sel_hi:[1,0]
	v_pk_add_f32 v[172:173], v[172:173], s[38:39] op_sel_hi:[1,0]
	v_pk_add_f32 v[174:175], v[174:175], s[38:39] op_sel_hi:[1,0]
	v_pk_add_f32 v[176:177], v[176:177], s[38:39] op_sel_hi:[1,0]
	v_rcp_f32_e32 v170, v170
	v_rcp_f32_e32 v171, v171
	v_rcp_f32_e32 v172, v172
	v_rcp_f32_e32 v173, v173
	v_rcp_f32_e32 v174, v174
	v_rcp_f32_e32 v175, v175
	v_rcp_f32_e32 v176, v176
	v_rcp_f32_e32 v177, v177
	v_pk_mul_f32 v[170:171], v[96:97], v[170:171]
	v_pk_mul_f32 v[172:173], v[98:99], v[172:173]
	v_pk_mul_f32 v[174:175], v[88:89], v[174:175]
	v_pk_mul_f32 v[176:177], v[90:91], v[176:177]
	v_pk_mul_f32 v[170:171], v[92:93], v[170:171]
	v_pk_mul_f32 v[172:173], v[94:95], v[172:173]
	v_pk_mul_f32 v[174:175], v[84:85], v[174:175]
	v_pk_mul_f32 v[176:177], v[86:87], v[176:177]
	v_cvt_pk_bf16_f32 v194, v170, v171
	v_cvt_pk_bf16_f32 v195, v172, v173
	v_cvt_pk_bf16_f32 v196, v174, v175
	v_cvt_pk_bf16_f32 v197, v176, v177
	global_store_dwordx4 v[156:157], v[194:197], off
	v_lshl_add_u64 v[156:157], v[156:157], 0, s[20:21]
	v_pk_mul_f32 v[76:77], v[76:77], v[138:139] op_sel_hi:[1,0]
	v_pk_mul_f32 v[78:79], v[78:79], v[138:139] op_sel_hi:[1,0]
	v_pk_mul_f32 v[68:69], v[68:69], v[138:139] op_sel_hi:[1,0]
	v_pk_mul_f32 v[70:71], v[70:71], v[138:139] op_sel_hi:[1,0]
	v_pk_mul_f32 v[72:73], v[72:73], v[138:139] op_sel_hi:[1,0]
	v_pk_mul_f32 v[74:75], v[74:75], v[138:139] op_sel_hi:[1,0]
	v_pk_mul_f32 v[64:65], v[64:65], v[138:139] op_sel_hi:[1,0]
	v_pk_mul_f32 v[66:67], v[66:67], v[138:139] op_sel_hi:[1,0]
	v_pk_mul_f32 v[178:179], v[76:77], s[82:83] op_sel_hi:[1,0]
	v_pk_mul_f32 v[180:181], v[78:79], s[82:83] op_sel_hi:[1,0]
	v_pk_mul_f32 v[182:183], v[68:69], s[82:83] op_sel_hi:[1,0]
	v_pk_mul_f32 v[184:185], v[70:71], s[82:83] op_sel_hi:[1,0]
	v_exp_f32_e32 v178, v178
	v_exp_f32_e32 v179, v179
	v_exp_f32_e32 v180, v180
	v_exp_f32_e32 v181, v181
	v_exp_f32_e32 v182, v182
	v_exp_f32_e32 v183, v183
	v_exp_f32_e32 v184, v184
	v_exp_f32_e32 v185, v185
	v_pk_add_f32 v[178:179], v[178:179], s[38:39] op_sel_hi:[1,0]
	v_pk_add_f32 v[180:181], v[180:181], s[38:39] op_sel_hi:[1,0]
	v_pk_add_f32 v[182:183], v[182:183], s[38:39] op_sel_hi:[1,0]
	v_pk_add_f32 v[184:185], v[184:185], s[38:39] op_sel_hi:[1,0]
	v_rcp_f32_e32 v178, v178
	v_rcp_f32_e32 v179, v179
	v_rcp_f32_e32 v180, v180
	v_rcp_f32_e32 v181, v181
	v_rcp_f32_e32 v182, v182
	v_rcp_f32_e32 v183, v183
	v_rcp_f32_e32 v184, v184
	v_rcp_f32_e32 v185, v185
	v_pk_mul_f32 v[178:179], v[76:77], v[178:179]
	v_pk_mul_f32 v[180:181], v[78:79], v[180:181]
	v_pk_mul_f32 v[182:183], v[68:69], v[182:183]
	v_pk_mul_f32 v[184:185], v[70:71], v[184:185]
	v_pk_mul_f32 v[178:179], v[72:73], v[178:179]
	v_pk_mul_f32 v[180:181], v[74:75], v[180:181]
	v_pk_mul_f32 v[182:183], v[64:65], v[182:183]
	v_pk_mul_f32 v[184:185], v[66:67], v[184:185]
	v_cvt_pk_bf16_f32 v198, v178, v179
	v_cvt_pk_bf16_f32 v199, v180, v181
	v_cvt_pk_bf16_f32 v200, v182, v183
	v_cvt_pk_bf16_f32 v201, v184, v185
	global_store_dwordx4 v[156:157], v[198:201], off
	v_lshl_add_u64 v[156:157], v[156:157], 0, s[30:31]
	v_pk_mul_f32 v[60:61], v[60:61], v[112:113] op_sel_hi:[1,0]
	v_pk_mul_f32 v[62:63], v[62:63], v[112:113] op_sel_hi:[1,0]
	v_pk_mul_f32 v[52:53], v[52:53], v[112:113] op_sel_hi:[1,0]
	v_pk_mul_f32 v[54:55], v[54:55], v[112:113] op_sel_hi:[1,0]
	v_pk_mul_f32 v[56:57], v[56:57], v[112:113] op_sel_hi:[1,0]
	v_pk_mul_f32 v[58:59], v[58:59], v[112:113] op_sel_hi:[1,0]
	v_pk_mul_f32 v[48:49], v[48:49], v[112:113] op_sel_hi:[1,0]
	v_pk_mul_f32 v[50:51], v[50:51], v[112:113] op_sel_hi:[1,0]
	v_pk_mul_f32 v[170:171], v[60:61], s[82:83] op_sel_hi:[1,0]
	v_pk_mul_f32 v[172:173], v[62:63], s[82:83] op_sel_hi:[1,0]
	v_pk_mul_f32 v[174:175], v[52:53], s[82:83] op_sel_hi:[1,0]
	v_pk_mul_f32 v[176:177], v[54:55], s[82:83] op_sel_hi:[1,0]
	v_exp_f32_e32 v170, v170
	v_exp_f32_e32 v171, v171
	v_exp_f32_e32 v172, v172
	v_exp_f32_e32 v173, v173
	v_exp_f32_e32 v174, v174
	v_exp_f32_e32 v175, v175
	v_exp_f32_e32 v176, v176
	v_exp_f32_e32 v177, v177
	v_pk_add_f32 v[170:171], v[170:171], s[38:39] op_sel_hi:[1,0]
	v_pk_add_f32 v[172:173], v[172:173], s[38:39] op_sel_hi:[1,0]
	v_pk_add_f32 v[174:175], v[174:175], s[38:39] op_sel_hi:[1,0]
	v_pk_add_f32 v[176:177], v[176:177], s[38:39] op_sel_hi:[1,0]
	v_rcp_f32_e32 v170, v170
	v_rcp_f32_e32 v171, v171
	v_rcp_f32_e32 v172, v172
	v_rcp_f32_e32 v173, v173
	v_rcp_f32_e32 v174, v174
	v_rcp_f32_e32 v175, v175
	v_rcp_f32_e32 v176, v176
	v_rcp_f32_e32 v177, v177
	v_pk_mul_f32 v[170:171], v[60:61], v[170:171]
	v_pk_mul_f32 v[172:173], v[62:63], v[172:173]
	v_pk_mul_f32 v[174:175], v[52:53], v[174:175]
	v_pk_mul_f32 v[176:177], v[54:55], v[176:177]
	v_pk_mul_f32 v[170:171], v[56:57], v[170:171]
	v_pk_mul_f32 v[172:173], v[58:59], v[172:173]
	v_pk_mul_f32 v[174:175], v[48:49], v[174:175]
	v_pk_mul_f32 v[176:177], v[50:51], v[176:177]
	v_cvt_pk_bf16_f32 v194, v170, v171
	v_cvt_pk_bf16_f32 v195, v172, v173
	v_cvt_pk_bf16_f32 v196, v174, v175
	v_cvt_pk_bf16_f32 v197, v176, v177
	global_store_dwordx4 v[156:157], v[194:197], off
	v_lshl_add_u64 v[156:157], v[156:157], 0, s[20:21]
	v_pk_mul_f32 v[44:45], v[44:45], v[114:115] op_sel_hi:[1,0]
	v_pk_mul_f32 v[46:47], v[46:47], v[114:115] op_sel_hi:[1,0]
	v_pk_mul_f32 v[36:37], v[36:37], v[114:115] op_sel_hi:[1,0]
	v_pk_mul_f32 v[38:39], v[38:39], v[114:115] op_sel_hi:[1,0]
	v_pk_mul_f32 v[40:41], v[40:41], v[114:115] op_sel_hi:[1,0]
	v_pk_mul_f32 v[42:43], v[42:43], v[114:115] op_sel_hi:[1,0]
	v_pk_mul_f32 v[32:33], v[32:33], v[114:115] op_sel_hi:[1,0]
	v_pk_mul_f32 v[34:35], v[34:35], v[114:115] op_sel_hi:[1,0]
	v_pk_mul_f32 v[178:179], v[44:45], s[82:83] op_sel_hi:[1,0]
	v_pk_mul_f32 v[180:181], v[46:47], s[82:83] op_sel_hi:[1,0]
	v_pk_mul_f32 v[182:183], v[36:37], s[82:83] op_sel_hi:[1,0]
	v_pk_mul_f32 v[184:185], v[38:39], s[82:83] op_sel_hi:[1,0]
	v_exp_f32_e32 v178, v178
	v_exp_f32_e32 v179, v179
	v_exp_f32_e32 v180, v180
	v_exp_f32_e32 v181, v181
	v_exp_f32_e32 v182, v182
	v_exp_f32_e32 v183, v183
	v_exp_f32_e32 v184, v184
	v_exp_f32_e32 v185, v185
	v_pk_add_f32 v[178:179], v[178:179], s[38:39] op_sel_hi:[1,0]
	v_pk_add_f32 v[180:181], v[180:181], s[38:39] op_sel_hi:[1,0]
	v_pk_add_f32 v[182:183], v[182:183], s[38:39] op_sel_hi:[1,0]
	v_pk_add_f32 v[184:185], v[184:185], s[38:39] op_sel_hi:[1,0]
	v_rcp_f32_e32 v178, v178
	v_rcp_f32_e32 v179, v179
	v_rcp_f32_e32 v180, v180
	v_rcp_f32_e32 v181, v181
	v_rcp_f32_e32 v182, v182
	v_rcp_f32_e32 v183, v183
	v_rcp_f32_e32 v184, v184
	v_rcp_f32_e32 v185, v185
	v_pk_mul_f32 v[178:179], v[44:45], v[178:179]
	v_pk_mul_f32 v[180:181], v[46:47], v[180:181]
	v_pk_mul_f32 v[182:183], v[36:37], v[182:183]
	v_pk_mul_f32 v[184:185], v[38:39], v[184:185]
	v_pk_mul_f32 v[178:179], v[40:41], v[178:179]
	v_pk_mul_f32 v[180:181], v[42:43], v[180:181]
	v_pk_mul_f32 v[182:183], v[32:33], v[182:183]
	v_pk_mul_f32 v[184:185], v[34:35], v[184:185]
	v_cvt_pk_bf16_f32 v198, v178, v179
	v_cvt_pk_bf16_f32 v199, v180, v181
	v_cvt_pk_bf16_f32 v200, v182, v183
	v_cvt_pk_bf16_f32 v201, v184, v185
	global_store_dwordx4 v[156:157], v[198:201], off
	v_lshl_add_u64 v[156:157], v[156:157], 0, s[20:21]
	v_pk_mul_f32 v[28:29], v[28:29], v[80:81] op_sel_hi:[1,0]
	v_pk_mul_f32 v[30:31], v[30:31], v[80:81] op_sel_hi:[1,0]
	v_pk_mul_f32 v[20:21], v[20:21], v[80:81] op_sel_hi:[1,0]
	v_pk_mul_f32 v[22:23], v[22:23], v[80:81] op_sel_hi:[1,0]
	v_pk_mul_f32 v[24:25], v[24:25], v[80:81] op_sel_hi:[1,0]
	v_pk_mul_f32 v[26:27], v[26:27], v[80:81] op_sel_hi:[1,0]
	v_pk_mul_f32 v[16:17], v[16:17], v[80:81] op_sel_hi:[1,0]
	v_pk_mul_f32 v[18:19], v[18:19], v[80:81] op_sel_hi:[1,0]
	v_pk_mul_f32 v[170:171], v[28:29], s[82:83] op_sel_hi:[1,0]
	v_pk_mul_f32 v[172:173], v[30:31], s[82:83] op_sel_hi:[1,0]
	v_pk_mul_f32 v[174:175], v[20:21], s[82:83] op_sel_hi:[1,0]
	v_pk_mul_f32 v[176:177], v[22:23], s[82:83] op_sel_hi:[1,0]
	v_exp_f32_e32 v170, v170
	v_exp_f32_e32 v171, v171
	v_exp_f32_e32 v172, v172
	v_exp_f32_e32 v173, v173
	v_exp_f32_e32 v174, v174
	v_exp_f32_e32 v175, v175
	v_exp_f32_e32 v176, v176
	v_exp_f32_e32 v177, v177
	v_pk_add_f32 v[170:171], v[170:171], s[38:39] op_sel_hi:[1,0]
	v_pk_add_f32 v[172:173], v[172:173], s[38:39] op_sel_hi:[1,0]
	v_pk_add_f32 v[174:175], v[174:175], s[38:39] op_sel_hi:[1,0]
	v_pk_add_f32 v[176:177], v[176:177], s[38:39] op_sel_hi:[1,0]
	v_rcp_f32_e32 v170, v170
	v_rcp_f32_e32 v171, v171
	v_rcp_f32_e32 v172, v172
	v_rcp_f32_e32 v173, v173
	v_rcp_f32_e32 v174, v174
	v_rcp_f32_e32 v175, v175
	v_rcp_f32_e32 v176, v176
	v_rcp_f32_e32 v177, v177
	v_pk_mul_f32 v[170:171], v[28:29], v[170:171]
	v_pk_mul_f32 v[172:173], v[30:31], v[172:173]
	v_pk_mul_f32 v[174:175], v[20:21], v[174:175]
	v_pk_mul_f32 v[176:177], v[22:23], v[176:177]
	v_pk_mul_f32 v[170:171], v[24:25], v[170:171]
	v_pk_mul_f32 v[172:173], v[26:27], v[172:173]
	v_pk_mul_f32 v[174:175], v[16:17], v[174:175]
	v_pk_mul_f32 v[176:177], v[18:19], v[176:177]
	v_cvt_pk_bf16_f32 v194, v170, v171
	v_cvt_pk_bf16_f32 v195, v172, v173
	v_cvt_pk_bf16_f32 v196, v174, v175
	v_cvt_pk_bf16_f32 v197, v176, v177
	global_store_dwordx4 v[156:157], v[194:197], off
	v_lshl_add_u64 v[156:157], v[156:157], 0, s[20:21]
	v_pk_mul_f32 v[12:13], v[12:13], v[82:83] op_sel_hi:[1,0]
	v_pk_mul_f32 v[14:15], v[14:15], v[82:83] op_sel_hi:[1,0]
	v_pk_mul_f32 v[4:5], v[4:5], v[82:83] op_sel_hi:[1,0]
	v_pk_mul_f32 v[6:7], v[6:7], v[82:83] op_sel_hi:[1,0]
	v_pk_mul_f32 v[8:9], v[8:9], v[82:83] op_sel_hi:[1,0]
	v_pk_mul_f32 v[10:11], v[10:11], v[82:83] op_sel_hi:[1,0]
	v_pk_mul_f32 v[0:1], v[0:1], v[82:83] op_sel_hi:[1,0]
	v_pk_mul_f32 v[2:3], v[2:3], v[82:83] op_sel_hi:[1,0]
	v_pk_mul_f32 v[178:179], v[12:13], s[82:83] op_sel_hi:[1,0]
	v_pk_mul_f32 v[180:181], v[14:15], s[82:83] op_sel_hi:[1,0]
	v_pk_mul_f32 v[182:183], v[4:5], s[82:83] op_sel_hi:[1,0]
	v_pk_mul_f32 v[184:185], v[6:7], s[82:83] op_sel_hi:[1,0]
	v_exp_f32_e32 v178, v178
	v_exp_f32_e32 v179, v179
	v_exp_f32_e32 v180, v180
	v_exp_f32_e32 v181, v181
	v_exp_f32_e32 v182, v182
	v_exp_f32_e32 v183, v183
	v_exp_f32_e32 v184, v184
	v_exp_f32_e32 v185, v185
	v_pk_add_f32 v[178:179], v[178:179], s[38:39] op_sel_hi:[1,0]
	v_pk_add_f32 v[180:181], v[180:181], s[38:39] op_sel_hi:[1,0]
	v_pk_add_f32 v[182:183], v[182:183], s[38:39] op_sel_hi:[1,0]
	v_pk_add_f32 v[184:185], v[184:185], s[38:39] op_sel_hi:[1,0]
	v_rcp_f32_e32 v178, v178
	v_rcp_f32_e32 v179, v179
	v_rcp_f32_e32 v180, v180
	v_rcp_f32_e32 v181, v181
	v_rcp_f32_e32 v182, v182
	v_rcp_f32_e32 v183, v183
	v_rcp_f32_e32 v184, v184
	v_rcp_f32_e32 v185, v185
	v_pk_mul_f32 v[178:179], v[12:13], v[178:179]
	v_pk_mul_f32 v[180:181], v[14:15], v[180:181]
	v_pk_mul_f32 v[182:183], v[4:5], v[182:183]
	v_pk_mul_f32 v[184:185], v[6:7], v[184:185]
	v_pk_mul_f32 v[178:179], v[8:9], v[178:179]
	v_pk_mul_f32 v[180:181], v[10:11], v[180:181]
	v_pk_mul_f32 v[182:183], v[0:1], v[182:183]
	v_pk_mul_f32 v[184:185], v[2:3], v[184:185]
	v_cvt_pk_bf16_f32 v198, v178, v179
	v_cvt_pk_bf16_f32 v199, v180, v181
	v_cvt_pk_bf16_f32 v200, v182, v183
	v_cvt_pk_bf16_f32 v201, v184, v185
	global_store_dwordx4 v[156:157], v[198:201], off
	s_and_b64 vcc, exec, s[8:9]
	s_cbranch_vccz .LBB0_666
	s_lshl_b32 s8, s16, 8
	s_lshl_b32 s3, s94, 11
	s_ashr_i32 s9, s8, 31
	s_and_b32 s3, s3, 0x800
	v_lshl_add_u64 v[0:1], s[8:9], 3, v[150:151]
	s_add_i32 m0, s46, s3
	s_nop 0
	global_load_lds_dwordx4 v[0:1], off
	s_branch .LBB0_666
	s_nop 0
	s_nop 0
	s_nop 0
	s_nop 0
	s_nop 0
	s_nop 0
	s_nop 0
	s_nop 0
	s_nop 0
	s_nop 0
	s_nop 0
	s_nop 0
	s_nop 0
	s_nop 0
	s_nop 0
	s_nop 0
	s_nop 0
	s_nop 0
	s_nop 0
	s_nop 0
	s_nop 0
	s_nop 0
	s_nop 0
	s_nop 0
	s_nop 0
	s_nop 0
	s_nop 0
	s_nop 0
	s_nop 0
	s_nop 0
